# gla_unit<1>: all loads of sub-chunk j+1 issued during sub-chunk j into otherwise unused registers (no exposed round trips in the sub-chunk loop)
# speedup vs baseline: 1.0007x; 1.0007x over previous
.LBB0_152:
	s_lshl_b32 s0, s22, 6
	s_and_b32 s8, s22, 3
	s_and_b32 s18, s0, 0xffffff00
	v_mov_b32_e32 v114, v216
	s_lshl_b32 s7, s8, 7
	s_lshl_b32 s10, s8, 9
	s_add_u32 s0, s2, s10
	v_and_b32_e32 v16, 0x7f, v114
	s_addc_u32 s1, s3, 0
	v_lshlrev_b32_e32 v0, 2, v16
	s_waitcnt lgkmcnt(0)
	v_lshl_add_u64 v[2:3], s[0:1], 0, v[0:1]
	v_add_co_u32_e32 v4, vcc, s34, v2
	s_movk_i32 s9, 0x2000
	s_nop 0
	v_addc_co_u32_e32 v5, vcc, 0, v3, vcc
	v_add_co_u32_e32 v6, vcc, s9, v2
	s_movk_i32 s9, 0x3000
	s_nop 0
	v_addc_co_u32_e32 v7, vcc, 0, v3, vcc
	v_add_co_u32_e32 v8, vcc, s9, v2
	s_movk_i32 s9, 0x5000
	s_nop 0
	v_addc_co_u32_e32 v9, vcc, 0, v3, vcc
	v_add_co_u32_e32 v10, vcc, s43, v2
	v_readlane_b32 s64, v254, 8
	s_nop 0
	v_addc_co_u32_e32 v11, vcc, 0, v3, vcc
	v_add_co_u32_e32 v12, vcc, s9, v2
	s_movk_i32 s9, 0x6000
	s_nop 0
	v_addc_co_u32_e32 v13, vcc, 0, v3, vcc
	v_add_co_u32_e32 v14, vcc, s9, v2
	v_readlane_b32 s76, v254, 20
	s_nop 0
	v_addc_co_u32_e32 v15, vcc, 0, v3, vcc
	global_load_dword v86, v[6:7], off offset:-4096
	global_load_dword v89, v[6:7], off
	global_load_dword v91, v[6:7], off offset:2048
	global_load_dword v87, v[10:11], off offset:-4096
	global_load_dword v92, v[10:11], off
	global_load_dword v94, v[10:11], off offset:2048
	global_load_dword v96, v[14:15], off offset:-4096
	global_load_dword v93, v[14:15], off
	global_load_dword v95, v[14:15], off offset:2048
	v_add_co_u32_e32 v2, vcc, s35, v2
	v_readlane_b32 s77, v254, 21
	s_nop 0
	v_addc_co_u32_e32 v3, vcc, 0, v3, vcc
	global_load_dword v88, v0, s[0:1]
	global_load_dword v90, v0, s[0:1] offset:2048
	global_load_dword v98, v[4:5], off offset:2048
	global_load_dword v99, v[8:9], off offset:2048
	global_load_dword v100, v[12:13], off offset:2048
	global_load_dword v97, v[2:3], off
	global_load_dword v101, v[2:3], off offset:2048
	s_or_b32 s0, s7, s4
	v_or_b32_e32 v2, s0, v16
	v_ashrrev_i32_e32 v3, 31, v2
	v_lshl_add_u64 v[2:3], v[2:3], 2, s[76:77]
	global_load_dword v117, v[2:3], off
	v_readfirstlane_b32 s6, v114
	s_ashr_i32 s26, s6, 6
	s_lshl_b32 s0, s8, 8
	v_readlane_b32 s1, v249, 22
	s_add_u32 s0, s1, s0
	v_readlane_b32 s1, v249, 23
	v_add_u32_e32 v120, 0, v0
	s_addc_u32 s1, s1, 0
	v_lshlrev_b32_e32 v0, 1, v16
	v_lshl_add_u64 v[102:103], s[0:1], 0, v[0:1]
	v_readlane_b32 s0, v249, 10
	v_and_b32_e32 v0, 15, v114
	s_add_u32 s24, s0, s10
	v_readlane_b32 s0, v249, 11
	v_and_b32_e32 v121, 48, v114
	v_mul_u32_u24_e32 v0, 0x90, v0
	s_addc_u32 s25, s0, 0
	v_add3_u32 v122, 0, v0, v121
	v_lshlrev_b32_e32 v0, 4, v114
	v_readlane_b32 s0, v249, 12
	v_add_u32_e32 v10, 0x200, v114
	v_add_u32_e32 v11, 0x400, v114
	v_add_u32_e32 v12, 0x600, v114
	v_and_b32_e32 v0, 48, v0
	v_readlane_b32 s1, v249, 13
	v_ashrrev_i32_e32 v9, 3, v114
	v_ashrrev_i32_e32 v10, 3, v10
	v_ashrrev_i32_e32 v11, 3, v11
	v_ashrrev_i32_e32 v12, 3, v12
	v_and_b32_e32 v116, 63, v114
	v_ashrrev_i32_e32 v2, 7, v114
	v_ashrrev_i32_e32 v6, 2, v114
	v_lshl_add_u64 v[104:105], s[0:1], 0, v[0:1]
	v_and_b32_e32 v106, -8, v9
	s_movk_i32 s0, 0x90
	v_and_b32_e32 v108, -8, v10
	v_and_b32_e32 v110, -8, v11
	v_and_b32_e32 v112, -8, v12
	v_mad_u32_u24 v3, v16, s40, v120
	v_lshlrev_b32_e32 v4, 5, v2
	v_lshl_add_u32 v5, v116, 1, 0
	v_lshl_add_u32 v7, v6, 6, 0
	v_mul_i32_i24_e32 v8, 0xffffff74, v16
	v_mul_lo_u32 v9, v106, s0
	v_mul_lo_u32 v10, v108, s0
	v_mul_lo_u32 v11, v110, s0
	v_mul_lo_u32 v12, v112, s0
	v_mov_b32_e32 v62, 0
	s_mov_b32 s5, 0
	v_cmp_gt_i32_e32 vcc, s42, v114
	v_cmp_gt_i32_e64 s[6:7], 64, v114
	v_lshl_add_u32 v118, v2, 10, 0
	v_lshl_add_u32 v119, v114, 2, 0
	v_cmp_gt_u32_e64 s[8:9], s27, v114
	v_cmp_lt_i32_e64 s[10:11], 0, v2
	v_cmp_lt_i32_e64 s[12:13], 1, v2
	v_cmp_lt_i32_e64 s[14:15], 2, v2
	v_cmp_lt_i32_e64 s[16:17], 3, v2
	v_ashrrev_i32_e32 v107, 31, v106
	v_ashrrev_i32_e32 v109, 31, v108
	v_ashrrev_i32_e32 v111, 31, v110
	v_ashrrev_i32_e32 v113, 31, v112
	v_add_u32_e32 v123, s18, v6
	s_waitcnt vmcnt(17)
	v_or_b32_e32 v124, s18, v116
	v_lshl_add_u32 v125, v2, 4, s18
	v_mov_b32_e32 v115, 1.0
	v_add_u32_e32 v126, v7, v0
	v_add_u32_e32 v127, v3, v4
	v_add_u32_e32 v128, v3, v8
	v_add_u32_e32 v129, v5, v9
	v_add_u32_e32 v130, v5, v10
	v_add_u32_e32 v131, v5, v11
	v_add_u32_e32 v132, v5, v12
	v_mov_b32_e32 v63, v62
	v_mov_b32_e32 v64, v62
	v_mov_b32_e32 v65, v62
	v_mov_b32_e32 v58, v62
	v_mov_b32_e32 v59, v62
	v_mov_b32_e32 v60, v62
	v_mov_b32_e32 v61, v62
	v_mov_b32_e32 v54, v62
	v_mov_b32_e32 v55, v62
	v_mov_b32_e32 v56, v62
	v_mov_b32_e32 v57, v62
	v_mov_b32_e32 v50, v62
	v_mov_b32_e32 v51, v62
	v_mov_b32_e32 v52, v62
	v_mov_b32_e32 v53, v62
	v_mov_b32_e32 v46, v62
	v_mov_b32_e32 v47, v62
	v_mov_b32_e32 v48, v62
	v_mov_b32_e32 v49, v62
	v_mov_b32_e32 v38, v62
	v_mov_b32_e32 v39, v62
	v_mov_b32_e32 v40, v62
	v_mov_b32_e32 v41, v62
	v_mov_b32_e32 v42, v62
	v_mov_b32_e32 v43, v62
	v_mov_b32_e32 v44, v62
	v_mov_b32_e32 v45, v62
	v_mov_b32_e32 v34, v62
	v_mov_b32_e32 v35, v62
	v_mov_b32_e32 v36, v62
	v_mov_b32_e32 v37, v62
	v_mov_b32_e32 v30, v62
	v_mov_b32_e32 v31, v62
	v_mov_b32_e32 v32, v62
	v_mov_b32_e32 v33, v62
	v_mov_b32_e32 v22, v62
	v_mov_b32_e32 v23, v62
	v_mov_b32_e32 v24, v62
	v_mov_b32_e32 v25, v62
	v_mov_b32_e32 v26, v62
	v_mov_b32_e32 v27, v62
	v_mov_b32_e32 v28, v62
	v_mov_b32_e32 v29, v62
	v_mov_b32_e32 v18, v62
	v_mov_b32_e32 v19, v62
	v_mov_b32_e32 v20, v62
	v_mov_b32_e32 v21, v62
	v_mov_b32_e32 v14, v62
	v_mov_b32_e32 v15, v62
	v_mov_b32_e32 v16, v62
	v_mov_b32_e32 v17, v62
	v_mov_b32_e32 v6, v62
	v_mov_b32_e32 v7, v62
	v_mov_b32_e32 v8, v62
	v_mov_b32_e32 v9, v62
	v_mov_b32_e32 v10, v62
	v_mov_b32_e32 v11, v62
	v_mov_b32_e32 v12, v62
	v_mov_b32_e32 v13, v62
	v_mov_b32_e32 v2, v62
	v_mov_b32_e32 v3, v62
	v_mov_b32_e32 v4, v62
	v_mov_b32_e32 v5, v62
	v_readlane_b32 s65, v254, 9
	v_readlane_b32 s66, v254, 10
	v_readlane_b32 s67, v254, 11
	v_readlane_b32 s68, v254, 12
	v_readlane_b32 s69, v254, 13
	v_readlane_b32 s70, v254, 14
	v_readlane_b32 s71, v254, 15
	v_readlane_b32 s72, v254, 16
	v_readlane_b32 s73, v254, 17
	v_readlane_b32 s74, v254, 18
	v_readlane_b32 s75, v254, 19
	v_readlane_b32 s78, v254, 22
	v_readlane_b32 s79, v254, 23
	s_mov_b64 exec, vcc
	v_add_u32_e32 v66, s5, v123
	v_ashrrev_i32_e32 v67, 31, v66
	v_lshlrev_b64 v[66:67], 8, v[66:67]
	v_lshl_add_u64 v[66:67], v[104:105], 0, v[66:67]
	global_load_dwordx4 v[174:177], v[66:67], off
	s_mov_b64 exec, -1
	v_add_u32_e32 v66, s5, v125
	v_ashrrev_i32_e32 v67, 31, v66
	v_lshlrev_b64 v[66:67], 11, v[66:67]
	v_lshl_add_u64 v[66:67], v[102:103], 0, v[66:67]
	v_mov_b32_e32 v72, 0x1000
	v_mov_b32_e32 v73, 0
	global_load_ushort v170, v[66:67], off
	global_load_ushort v171, v[66:67], off offset:2048
	v_lshl_add_u64 v[66:67], v[66:67], 0, v[72:73]
	global_load_ushort v172, v[66:67], off
	global_load_ushort v178, v[66:67], off offset:2048
	v_lshl_add_u64 v[66:67], v[66:67], 0, v[72:73]
	global_load_ushort v181, v[66:67], off
	global_load_ushort v202, v[66:67], off offset:2048
	v_lshl_add_u64 v[66:67], v[66:67], 0, v[72:73]
	global_load_ushort v203, v[66:67], off
	global_load_ushort v225, v[66:67], off offset:2048
	v_lshl_add_u64 v[66:67], v[66:67], 0, v[72:73]
	global_load_ushort v230, v[66:67], off
	global_load_ushort v231, v[66:67], off offset:2048
	v_lshl_add_u64 v[66:67], v[66:67], 0, v[72:73]
	global_load_ushort v236, v[66:67], off
	global_load_ushort v237, v[66:67], off offset:2048
	v_lshl_add_u64 v[66:67], v[66:67], 0, v[72:73]
	global_load_ushort v238, v[66:67], off
	global_load_ushort v241, v[66:67], off offset:2048
	v_lshl_add_u64 v[66:67], v[66:67], 0, v[72:73]
	global_load_ushort v242, v[66:67], off
	global_load_ushort v243, v[66:67], off offset:2048
	v_add_u32_e32 v66, s5, v124
	v_ashrrev_i32_e32 v67, 31, v66
	v_lshlrev_b64 v[66:67], 11, v[66:67]
	v_lshl_add_u64 v[70:71], s[24:25], 0, v[66:67]
	v_lshl_add_u64 v[66:67], v[106:107], 1, v[70:71]
	global_load_dwordx4 v[142:145], v[66:67], off
	v_lshl_add_u64 v[66:67], v[108:109], 1, v[70:71]
	global_load_dwordx4 v[146:149], v[66:67], off
	v_lshl_add_u64 v[66:67], v[110:111], 1, v[70:71]
	global_load_dwordx4 v[232:235], v[66:67], off
	v_lshl_add_u64 v[66:67], v[112:113], 1, v[70:71]
	global_load_dwordx4 v[244:247], v[66:67], off
	s_branch .LBB0_154
.LBB0_153:
	s_or_b64 exec, exec, s[0:1]
	v_add_u32_e32 v66, s5, v124
	v_ashrrev_i32_e32 v67, 31, v66
	v_lshlrev_b64 v[66:67], 11, v[66:67]
	v_lshl_add_u64 v[70:71], s[24:25], 0, v[66:67]
	v_lshl_add_u64 v[66:67], v[106:107], 1, v[70:71]
	v_mov_b32_e32 v66, v142
	v_mov_b32_e32 v67, v143
	v_mov_b32_e32 v68, v144
	v_mov_b32_e32 v69, v145
	v_add_u32_e32 v0, 0, v121
	s_mul_i32 s0, s26, 0x1200
	v_add_u32_e32 v133, s0, v122
	s_add_i32 s5, s5, 64
	s_cmpk_eq_i32 s5, 0x100
	s_waitcnt vmcnt(0)
	ds_write_b16 v129, v66 offset:61952
	ds_write_b16_d16_hi v129, v66 offset:62096
	ds_write_b16 v129, v67 offset:62240
	ds_write_b16_d16_hi v129, v67 offset:62384
	ds_write_b16 v129, v68 offset:62528
	ds_write_b16_d16_hi v129, v68 offset:62672
	ds_write_b16 v129, v69 offset:62816
	ds_write_b16_d16_hi v129, v69 offset:62960
	v_lshl_add_u64 v[66:67], v[108:109], 1, v[70:71]
	v_mov_b32_e32 v66, v146
	v_mov_b32_e32 v67, v147
	v_mov_b32_e32 v68, v148
	v_mov_b32_e32 v69, v149
	s_waitcnt vmcnt(0)
	ds_write_b16 v130, v66 offset:61952
	ds_write_b16_d16_hi v130, v66 offset:62096
	ds_write_b16 v130, v67 offset:62240
	ds_write_b16_d16_hi v130, v67 offset:62384
	ds_write_b16 v130, v68 offset:62528
	ds_write_b16_d16_hi v130, v68 offset:62672
	ds_write_b16 v130, v69 offset:62816
	ds_write_b16_d16_hi v130, v69 offset:62960
	v_lshl_add_u64 v[66:67], v[110:111], 1, v[70:71]
	v_mov_b32_e32 v66, v232
	v_mov_b32_e32 v67, v233
	v_mov_b32_e32 v68, v234
	v_mov_b32_e32 v69, v235
	s_waitcnt vmcnt(0)
	ds_write_b16 v131, v66 offset:61952
	ds_write_b16_d16_hi v131, v66 offset:62096
	ds_write_b16 v131, v67 offset:62240
	ds_write_b16_d16_hi v131, v67 offset:62384
	ds_write_b16 v131, v68 offset:62528
	ds_write_b16_d16_hi v131, v68 offset:62672
	ds_write_b16 v131, v69 offset:62816
	ds_write_b16_d16_hi v131, v69 offset:62960
	v_lshl_add_u64 v[66:67], v[112:113], 1, v[70:71]
	v_mov_b32_e32 v66, v244
	v_mov_b32_e32 v67, v245
	v_mov_b32_e32 v68, v246
	v_mov_b32_e32 v69, v247
	s_waitcnt vmcnt(0)
	ds_write_b16 v132, v66 offset:61952
	ds_write_b16_d16_hi v132, v66 offset:62096
	ds_write_b16 v132, v67 offset:62240
	ds_write_b16_d16_hi v132, v67 offset:62384
	ds_write_b16 v132, v68 offset:62528
	ds_write_b16_d16_hi v132, v68 offset:62672
	ds_write_b16 v132, v69 offset:62816
	ds_write_b16_d16_hi v132, v69 offset:62960
	s_cbranch_scc1 .Lg1pf_skip
	s_mov_b64 exec, vcc
	v_add_u32_e32 v66, s5, v123
	v_ashrrev_i32_e32 v67, 31, v66
	v_lshlrev_b64 v[66:67], 8, v[66:67]
	v_lshl_add_u64 v[66:67], v[104:105], 0, v[66:67]
	global_load_dwordx4 v[174:177], v[66:67], off
	s_mov_b64 exec, -1
	v_add_u32_e32 v66, s5, v125
	v_ashrrev_i32_e32 v67, 31, v66
	v_lshlrev_b64 v[66:67], 11, v[66:67]
	v_lshl_add_u64 v[66:67], v[102:103], 0, v[66:67]
	v_mov_b32_e32 v72, 0x1000
	v_mov_b32_e32 v73, 0
	global_load_ushort v170, v[66:67], off
	global_load_ushort v171, v[66:67], off offset:2048
	v_lshl_add_u64 v[66:67], v[66:67], 0, v[72:73]
	global_load_ushort v172, v[66:67], off
	global_load_ushort v178, v[66:67], off offset:2048
	v_lshl_add_u64 v[66:67], v[66:67], 0, v[72:73]
	global_load_ushort v181, v[66:67], off
	global_load_ushort v202, v[66:67], off offset:2048
	v_lshl_add_u64 v[66:67], v[66:67], 0, v[72:73]
	global_load_ushort v203, v[66:67], off
	global_load_ushort v225, v[66:67], off offset:2048
	v_lshl_add_u64 v[66:67], v[66:67], 0, v[72:73]
	global_load_ushort v230, v[66:67], off
	global_load_ushort v231, v[66:67], off offset:2048
	v_lshl_add_u64 v[66:67], v[66:67], 0, v[72:73]
	global_load_ushort v236, v[66:67], off
	global_load_ushort v237, v[66:67], off offset:2048
	v_lshl_add_u64 v[66:67], v[66:67], 0, v[72:73]
	global_load_ushort v238, v[66:67], off
	global_load_ushort v241, v[66:67], off offset:2048
	v_lshl_add_u64 v[66:67], v[66:67], 0, v[72:73]
	global_load_ushort v242, v[66:67], off
	global_load_ushort v243, v[66:67], off offset:2048
	v_add_u32_e32 v66, s5, v124
	v_ashrrev_i32_e32 v67, 31, v66
	v_lshlrev_b64 v[66:67], 11, v[66:67]
	v_lshl_add_u64 v[70:71], s[24:25], 0, v[66:67]
	v_lshl_add_u64 v[66:67], v[106:107], 1, v[70:71]
	global_load_dwordx4 v[142:145], v[66:67], off
	v_lshl_add_u64 v[66:67], v[108:109], 1, v[70:71]
	global_load_dwordx4 v[146:149], v[66:67], off
	v_lshl_add_u64 v[66:67], v[110:111], 1, v[70:71]
	global_load_dwordx4 v[232:235], v[66:67], off
	v_lshl_add_u64 v[66:67], v[112:113], 1, v[70:71]
	global_load_dwordx4 v[244:247], v[66:67], off
.Lg1pf_skip:
	s_waitcnt lgkmcnt(0)
	s_barrier
	ds_read_b128 v[66:69], v0 offset:6144
	ds_read_b128 v[78:81], v122 offset:43520
	ds_read_b128 v[82:85], v122 offset:43584
	ds_read_b128 v[70:73], v133 offset:62016
	s_waitcnt lgkmcnt(3)
	v_mul_f32_e32 v66, 0x3fb8aa3b, v66
	v_exp_f32_e32 v74, v66
	v_mul_f32_e32 v66, 0x3fb8aa3b, v67
	v_exp_f32_e32 v75, v66
	v_mul_f32_e32 v66, 0x3fb8aa3b, v68
	v_exp_f32_e32 v76, v66
	v_mul_f32_e32 v66, 0x3fb8aa3b, v69
	v_exp_f32_e32 v77, v66
	v_pk_mul_f32 v[62:63], v[62:63], v[74:75]
	ds_read_b128 v[66:69], v133 offset:61952
	v_pk_mul_f32 v[58:59], v[58:59], v[74:75]
	v_pk_mul_f32 v[64:65], v[64:65], v[76:77]
	v_pk_mul_f32 v[60:61], v[60:61], v[76:77]
	ds_read_b128 v[74:77], v133 offset:64256
	s_waitcnt lgkmcnt(1)
	v_mfma_f32_16x16x32_bf16 v[62:65], v[78:81], v[66:69], v[62:65]
	s_waitcnt lgkmcnt(0)
	v_mfma_f32_16x16x32_bf16 v[58:61], v[78:81], v[74:77], v[58:61]
	ds_read_b128 v[78:81], v133 offset:64320
	v_mfma_f32_16x16x32_bf16 v[62:65], v[82:85], v[70:73], v[62:65]
	s_waitcnt lgkmcnt(0)
	v_mfma_f32_16x16x32_bf16 v[58:61], v[82:85], v[78:81], v[58:61]
	ds_read_b128 v[82:85], v0 offset:6208
	s_waitcnt lgkmcnt(0)
	v_mul_f32_e32 v82, 0x3fb8aa3b, v82
	v_exp_f32_e32 v138, v82
	v_mul_f32_e32 v82, 0x3fb8aa3b, v83
	v_exp_f32_e32 v139, v82
	v_mul_f32_e32 v82, 0x3fb8aa3b, v84
	v_exp_f32_e32 v140, v82
	v_mul_f32_e32 v82, 0x3fb8aa3b, v85
	v_exp_f32_e32 v141, v82
	ds_read_b128 v[82:85], v122 offset:45824
	ds_read_b128 v[134:137], v122 offset:45888
	v_pk_mul_f32 v[54:55], v[54:55], v[138:139]
	v_pk_mul_f32 v[50:51], v[50:51], v[138:139]
	v_pk_mul_f32 v[56:57], v[56:57], v[140:141]
	v_pk_mul_f32 v[52:53], v[52:53], v[140:141]
	s_waitcnt lgkmcnt(1)
	v_mfma_f32_16x16x32_bf16 v[54:57], v[82:85], v[66:69], v[54:57]
	v_mfma_f32_16x16x32_bf16 v[50:53], v[82:85], v[74:77], v[50:53]
	ds_read_b128 v[82:85], v0 offset:6272
	s_waitcnt lgkmcnt(0)
	v_mul_f32_e32 v82, 0x3fb8aa3b, v82
	v_exp_f32_e32 v138, v82
	v_mul_f32_e32 v82, 0x3fb8aa3b, v83
	v_exp_f32_e32 v139, v82
	v_mul_f32_e32 v82, 0x3fb8aa3b, v84
	v_exp_f32_e32 v140, v82
	v_mul_f32_e32 v82, 0x3fb8aa3b, v85
	v_exp_f32_e32 v141, v82
	v_mfma_f32_16x16x32_bf16 v[54:57], v[134:137], v[70:73], v[54:57]
	v_mul_f32_e64 v46, v46, v138
	v_mul_f32_e64 v47, v47, v139
	v_pk_mul_f32 v[38:39], v[38:39], v[138:139]
	v_pk_mul_f32 v[48:49], v[48:49], v[140:141]
	v_mfma_f32_16x16x32_bf16 v[50:53], v[134:137], v[78:81], v[50:53]
	ds_read_b128 v[82:85], v122 offset:48128
	ds_read_b128 v[134:137], v122 offset:48192
	v_pk_mul_f32 v[40:41], v[40:41], v[140:141]
	s_waitcnt lgkmcnt(1)
	v_mfma_f32_16x16x32_bf16 v[46:49], v[82:85], v[66:69], v[46:49]
	v_mfma_f32_16x16x32_bf16 v[38:41], v[82:85], v[74:77], v[38:41]
	ds_read_b128 v[82:85], v0 offset:6336
	s_waitcnt lgkmcnt(0)
	v_mul_f32_e32 v82, 0x3fb8aa3b, v82
	v_exp_f32_e32 v138, v82
	v_mul_f32_e32 v82, 0x3fb8aa3b, v83
	v_exp_f32_e32 v139, v82
	v_mul_f32_e32 v82, 0x3fb8aa3b, v84
	v_exp_f32_e32 v140, v82
	v_mul_f32_e32 v82, 0x3fb8aa3b, v85
	v_exp_f32_e32 v141, v82
	v_mfma_f32_16x16x32_bf16 v[46:49], v[134:137], v[70:73], v[46:49]
	v_mul_f32_e64 v42, v42, v138
	v_mul_f32_e64 v43, v43, v139
	v_pk_mul_f32 v[34:35], v[34:35], v[138:139]
	v_pk_mul_f32 v[44:45], v[44:45], v[140:141]
	v_mfma_f32_16x16x32_bf16 v[38:41], v[134:137], v[78:81], v[38:41]
	ds_read_b128 v[82:85], v122 offset:50432
	ds_read_b128 v[134:137], v122 offset:50496
	v_pk_mul_f32 v[36:37], v[36:37], v[140:141]
	s_waitcnt lgkmcnt(1)
	v_mfma_f32_16x16x32_bf16 v[42:45], v[82:85], v[66:69], v[42:45]
	v_mfma_f32_16x16x32_bf16 v[34:37], v[82:85], v[74:77], v[34:37]
	ds_read_b128 v[82:85], v0 offset:6400
	s_waitcnt lgkmcnt(0)
	v_mul_f32_e32 v82, 0x3fb8aa3b, v82
	v_exp_f32_e32 v138, v82
	v_mul_f32_e32 v82, 0x3fb8aa3b, v83
	v_exp_f32_e32 v139, v82
	v_mul_f32_e32 v82, 0x3fb8aa3b, v84
	v_exp_f32_e32 v140, v82
	v_mul_f32_e32 v82, 0x3fb8aa3b, v85
	v_exp_f32_e32 v141, v82
	v_mfma_f32_16x16x32_bf16 v[42:45], v[134:137], v[70:73], v[42:45]
	v_mul_f32_e64 v30, v30, v138
	v_mul_f32_e64 v31, v31, v139
	v_pk_mul_f32 v[22:23], v[22:23], v[138:139]
	v_pk_mul_f32 v[32:33], v[32:33], v[140:141]
	v_mfma_f32_16x16x32_bf16 v[34:37], v[134:137], v[78:81], v[34:37]
	ds_read_b128 v[82:85], v122 offset:52736
	ds_read_b128 v[134:137], v122 offset:52800
	v_pk_mul_f32 v[24:25], v[24:25], v[140:141]
	s_waitcnt lgkmcnt(1)
	v_mfma_f32_16x16x32_bf16 v[30:33], v[82:85], v[66:69], v[30:33]
	v_mfma_f32_16x16x32_bf16 v[22:25], v[82:85], v[74:77], v[22:25]
	ds_read_b128 v[82:85], v0 offset:6464
	s_waitcnt lgkmcnt(0)
	v_mul_f32_e32 v82, 0x3fb8aa3b, v82
	v_exp_f32_e32 v138, v82
	v_mul_f32_e32 v82, 0x3fb8aa3b, v83
	v_exp_f32_e32 v139, v82
	v_mul_f32_e32 v82, 0x3fb8aa3b, v84
	v_exp_f32_e32 v140, v82
	v_mul_f32_e32 v82, 0x3fb8aa3b, v85
	v_exp_f32_e32 v141, v82
	v_mfma_f32_16x16x32_bf16 v[30:33], v[134:137], v[70:73], v[30:33]
	v_mul_f32_e64 v26, v26, v138
	v_mul_f32_e64 v27, v27, v139
	v_pk_mul_f32 v[18:19], v[18:19], v[138:139]
	v_pk_mul_f32 v[28:29], v[28:29], v[140:141]
	v_mfma_f32_16x16x32_bf16 v[22:25], v[134:137], v[78:81], v[22:25]
	ds_read_b128 v[82:85], v122 offset:55040
	ds_read_b128 v[134:137], v122 offset:55104
	v_pk_mul_f32 v[20:21], v[20:21], v[140:141]
	s_waitcnt lgkmcnt(1)
	v_mfma_f32_16x16x32_bf16 v[26:29], v[82:85], v[66:69], v[26:29]
	v_mfma_f32_16x16x32_bf16 v[18:21], v[82:85], v[74:77], v[18:21]
	ds_read_b128 v[82:85], v0 offset:6528
	s_waitcnt lgkmcnt(0)
	v_mul_f32_e32 v82, 0x3fb8aa3b, v82
	v_exp_f32_e32 v138, v82
	v_mul_f32_e32 v82, 0x3fb8aa3b, v83
	v_exp_f32_e32 v139, v82
	v_mul_f32_e32 v82, 0x3fb8aa3b, v84
	v_exp_f32_e32 v140, v82
	v_mul_f32_e32 v82, 0x3fb8aa3b, v85
	v_exp_f32_e32 v141, v82
	v_mfma_f32_16x16x32_bf16 v[26:29], v[134:137], v[70:73], v[26:29]
	v_mul_f32_e64 v14, v14, v138
	v_mul_f32_e64 v15, v15, v139
	v_pk_mul_f32 v[6:7], v[6:7], v[138:139]
	v_pk_mul_f32 v[16:17], v[16:17], v[140:141]
	v_mfma_f32_16x16x32_bf16 v[18:21], v[134:137], v[78:81], v[18:21]
	ds_read_b128 v[82:85], v122 offset:57344
	ds_read_b128 v[134:137], v122 offset:57408
	v_pk_mul_f32 v[8:9], v[8:9], v[140:141]
	s_waitcnt lgkmcnt(1)
	v_mfma_f32_16x16x32_bf16 v[14:17], v[82:85], v[66:69], v[14:17]
	v_mfma_f32_16x16x32_bf16 v[6:9], v[82:85], v[74:77], v[6:9]
	ds_read_b128 v[82:85], v0 offset:6592
	s_waitcnt lgkmcnt(0)
	v_mul_f32_e32 v0, 0x3fb8aa3b, v82
	v_exp_f32_e32 v138, v0
	v_mul_f32_e32 v0, 0x3fb8aa3b, v83
	v_exp_f32_e32 v139, v0
	v_mul_f32_e32 v0, 0x3fb8aa3b, v84
	v_exp_f32_e32 v140, v0
	v_mul_f32_e32 v0, 0x3fb8aa3b, v85
	v_exp_f32_e32 v141, v0
	v_mfma_f32_16x16x32_bf16 v[14:17], v[134:137], v[70:73], v[14:17]
	v_mul_f32_e64 v10, v10, v138
	v_mul_f32_e64 v11, v11, v139
	v_pk_mul_f32 v[2:3], v[2:3], v[138:139]
	v_pk_mul_f32 v[12:13], v[12:13], v[140:141]
	v_mfma_f32_16x16x32_bf16 v[6:9], v[134:137], v[78:81], v[6:9]
	ds_read_b128 v[82:85], v122 offset:59648
	ds_read_b128 v[134:137], v122 offset:59712
	v_pk_mul_f32 v[4:5], v[4:5], v[140:141]
	s_waitcnt lgkmcnt(0)
	v_mfma_f32_16x16x32_bf16 v[10:13], v[82:85], v[66:69], v[10:13]
	s_barrier
	v_mfma_f32_16x16x32_bf16 v[2:5], v[82:85], v[74:77], v[2:5]
	v_mfma_f32_16x16x32_bf16 v[10:13], v[134:137], v[70:73], v[10:13]
	v_mfma_f32_16x16x32_bf16 v[2:5], v[134:137], v[78:81], v[2:5]
	s_cbranch_scc1 .LBB0_160
.LBB0_154:
	s_and_saveexec_b64 s[0:1], vcc
	s_cbranch_execz .LBB0_156
	s_waitcnt vmcnt(20)
	v_mov_b32_e32 v66, v174
	v_mov_b32_e32 v67, v175
	v_mov_b32_e32 v68, v176
	v_mov_b32_e32 v69, v177
	ds_write_b128 v126, v[66:69]
.LBB0_156:
	s_or_b64 exec, exec, s[0:1]
	s_and_saveexec_b64 s[0:1], s[6:7]
	ds_write_b32 v119, v1 offset:6656
	s_or_b64 exec, exec, s[0:1]
	s_waitcnt lgkmcnt(0)
	s_barrier
	ds_read_b128 v[66:69], v118
	ds_read_b128 v[70:73], v118 offset:16
	ds_read_b128 v[74:77], v118 offset:32
	ds_read_b128 v[78:81], v118 offset:48
	s_mov_b32 s23, 0x800000
	s_waitcnt lgkmcnt(3)
	v_mov_b32_e32 v82, v66
	s_waitcnt lgkmcnt(2)
	v_mov_b32_e32 v83, v70
	v_mov_b32_e32 v70, v67
	s_waitcnt vmcnt(6)
	v_pk_mul_f32 v[66:67], v[90:91], v[70:71]
	v_mov_b32_e32 v70, v68
	v_pk_fma_f32 v[66:67], v[88:89], v[82:83], v[66:67]
	v_mov_b32_e32 v71, v72
	v_pk_fma_f32 v[66:67], v[86:87], v[70:71], v[66:67]
	v_mov_b32_e32 v72, v69
	s_waitcnt vmcnt(4)
	v_pk_fma_f32 v[66:67], v[98:99], v[72:73], v[66:67]
	s_waitcnt vmcnt(0)
	v_add_f32_e32 v0, v117, v66
	v_add_f32_e32 v0, v0, v67
	s_waitcnt lgkmcnt(0)
	v_mov_b32_e32 v67, v78
	v_mov_b32_e32 v78, v75
	v_mov_b32_e32 v66, v74
	v_pk_mul_f32 v[68:69], v[94:95], v[78:79]
	s_nop 0
	v_pk_fma_f32 v[66:67], v[92:93], v[66:67], v[68:69]
	v_mov_b32_e32 v68, v76
	v_mov_b32_e32 v69, v80
	v_pk_fma_f32 v[66:67], v[96:97], v[68:69], v[66:67]
	v_mov_b32_e32 v80, v77
	v_pk_fma_f32 v[66:67], v[100:101], v[80:81], v[66:67]
	ds_read_b128 v[68:71], v118 offset:64
	ds_read_b128 v[72:75], v118 offset:80
	v_add_f32_e32 v0, v0, v66
	v_add_f32_e32 v0, v0, v67
	v_min_f32_e32 v66, 0, v0
	v_mul_f32_e64 v0, |v0|, s30
	v_exp_f32_e32 v0, v0
	s_waitcnt lgkmcnt(0)
	v_mov_b32_e32 v77, v72
	v_mov_b32_e32 v72, v69
	v_mov_b32_e32 v76, v68
	v_add_f32_e32 v0, 1.0, v0
	v_cmp_gt_f32_e64 s[0:1], s23, v0
	v_pk_mul_f32 v[68:69], v[90:91], v[72:73]
	v_mov_b32_e32 v72, v70
	v_cndmask_b32_e64 v67, 0, 32, s[0:1]
	v_ldexp_f32 v0, v0, v67
	v_log_f32_e32 v0, v0
	v_pk_fma_f32 v[68:69], v[88:89], v[76:77], v[68:69]
	v_mov_b32_e32 v73, v74
	v_pk_fma_f32 v[68:69], v[86:87], v[72:73], v[68:69]
	v_mul_f32_e32 v67, 0x3f317217, v0
	v_fma_f32 v67, v0, s31, -v67
	v_fmac_f32_e32 v67, 0x3377d1cf, v0
	v_fmac_f32_e32 v67, 0x3f317217, v0
	v_cmp_lt_f32_e64 s[18:19], |v0|, s41
	v_mov_b32_e32 v74, v71
	v_pk_fma_f32 v[68:69], v[98:99], v[74:75], v[68:69]
	v_cndmask_b32_e64 v0, v0, v67, s[18:19]
	v_cndmask_b32_e64 v67, 0, v223, s[0:1]
	v_sub_f32_e32 v0, v0, v67
	v_sub_f32_e32 v0, v66, v0
	s_mov_b32 s0, 0x3d800000
	v_fma_f32 v66, v0, s0, 0
	v_add_f32_e32 v0, v117, v68
	v_add_f32_e32 v0, v0, v69
	ds_read_b128 v[68:71], v118 offset:96
	ds_read_b128 v[72:75], v118 offset:112
	s_waitcnt lgkmcnt(1)
	v_mov_b32_e32 v76, v68
	s_waitcnt lgkmcnt(0)
	v_mov_b32_e32 v77, v72
	v_mov_b32_e32 v72, v69
	v_pk_mul_f32 v[68:69], v[94:95], v[72:73]
	v_mov_b32_e32 v72, v70
	v_pk_fma_f32 v[68:69], v[92:93], v[76:77], v[68:69]
	v_mov_b32_e32 v73, v74
	v_pk_fma_f32 v[68:69], v[96:97], v[72:73], v[68:69]
	v_mov_b32_e32 v74, v71
	v_pk_fma_f32 v[68:69], v[100:101], v[74:75], v[68:69]
	s_nop 0
	v_add_f32_e32 v0, v0, v68
	v_add_f32_e32 v0, v0, v69
	v_min_f32_e32 v67, 0, v0
	v_mul_f32_e64 v0, |v0|, s30
	v_exp_f32_e32 v0, v0
	s_nop 0
	v_add_f32_e32 v0, 1.0, v0
	v_cmp_gt_f32_e64 s[0:1], s23, v0
	s_nop 1
	v_cndmask_b32_e64 v68, 0, 32, s[0:1]
	v_ldexp_f32 v0, v0, v68
	v_log_f32_e32 v0, v0
	s_nop 0
	v_mul_f32_e32 v68, 0x3f317217, v0
	v_fma_f32 v68, v0, s31, -v68
	v_fmac_f32_e32 v68, 0x3377d1cf, v0
	v_fmac_f32_e32 v68, 0x3f317217, v0
	v_cmp_lt_f32_e64 s[18:19], |v0|, s41
	s_nop 1
	v_cndmask_b32_e64 v0, v0, v68, s[18:19]
	v_cndmask_b32_e64 v68, 0, v223, s[0:1]
	v_sub_f32_e32 v0, v0, v68
	ds_read_b128 v[68:71], v118 offset:128
	ds_read_b128 v[72:75], v118 offset:144
	v_sub_f32_e32 v0, v67, v0
	v_fmamk_f32 v67, v0, 0x3d800000, v66
	s_waitcnt lgkmcnt(1)
	v_mov_b32_e32 v76, v68
	s_waitcnt lgkmcnt(0)
	v_mov_b32_e32 v77, v72
	v_mov_b32_e32 v72, v69
	v_pk_mul_f32 v[68:69], v[90:91], v[72:73]
	v_mov_b32_e32 v72, v70
	v_pk_fma_f32 v[68:69], v[88:89], v[76:77], v[68:69]
	v_mov_b32_e32 v73, v74
	v_pk_fma_f32 v[68:69], v[86:87], v[72:73], v[68:69]
	v_mov_b32_e32 v74, v71
	v_pk_fma_f32 v[68:69], v[98:99], v[74:75], v[68:69]
	s_nop 0
	v_add_f32_e32 v0, v117, v68
	v_add_f32_e32 v0, v0, v69
	ds_read_b128 v[68:71], v118 offset:160
	ds_read_b128 v[72:75], v118 offset:176
	s_waitcnt lgkmcnt(1)
	v_mov_b32_e32 v76, v68
	s_waitcnt lgkmcnt(0)
	v_mov_b32_e32 v77, v72
	v_mov_b32_e32 v72, v69
	v_pk_mul_f32 v[68:69], v[94:95], v[72:73]
	v_mov_b32_e32 v72, v70
	v_pk_fma_f32 v[68:69], v[92:93], v[76:77], v[68:69]
	v_mov_b32_e32 v73, v74
	v_pk_fma_f32 v[68:69], v[96:97], v[72:73], v[68:69]
	v_mov_b32_e32 v74, v71
	v_pk_fma_f32 v[68:69], v[100:101], v[74:75], v[68:69]
	ds_read_b128 v[70:73], v118 offset:192
	ds_read_b128 v[74:77], v118 offset:208
	v_add_f32_e32 v0, v0, v68
	v_add_f32_e32 v0, v0, v69
	v_min_f32_e32 v68, 0, v0
	v_mul_f32_e64 v0, |v0|, s30
	v_exp_f32_e32 v0, v0
	s_waitcnt lgkmcnt(0)
	v_mov_b32_e32 v79, v74
	v_mov_b32_e32 v74, v71
	v_mov_b32_e32 v78, v70
	v_add_f32_e32 v0, 1.0, v0
	v_cmp_gt_f32_e64 s[0:1], s23, v0
	v_pk_mul_f32 v[70:71], v[90:91], v[74:75]
	v_mov_b32_e32 v74, v72
	v_cndmask_b32_e64 v69, 0, 32, s[0:1]
	v_ldexp_f32 v0, v0, v69
	v_log_f32_e32 v0, v0
	v_pk_fma_f32 v[70:71], v[88:89], v[78:79], v[70:71]
	v_mov_b32_e32 v75, v76
	v_pk_fma_f32 v[70:71], v[86:87], v[74:75], v[70:71]
	v_mul_f32_e32 v69, 0x3f317217, v0
	v_fma_f32 v69, v0, s31, -v69
	v_fmac_f32_e32 v69, 0x3377d1cf, v0
	v_fmac_f32_e32 v69, 0x3f317217, v0
	v_cmp_lt_f32_e64 s[18:19], |v0|, s41
	v_mov_b32_e32 v76, v73
	v_pk_fma_f32 v[70:71], v[98:99], v[76:77], v[70:71]
	v_cndmask_b32_e64 v0, v0, v69, s[18:19]
	v_cndmask_b32_e64 v69, 0, v223, s[0:1]
	v_sub_f32_e32 v0, v0, v69
	v_sub_f32_e32 v0, v68, v0
	v_fmamk_f32 v68, v0, 0x3d800000, v67
	v_add_f32_e32 v0, v117, v70
	v_add_f32_e32 v0, v0, v71
	ds_read_b128 v[70:73], v118 offset:224
	ds_read_b128 v[74:77], v118 offset:240
	s_waitcnt lgkmcnt(1)
	v_mov_b32_e32 v78, v70
	s_waitcnt lgkmcnt(0)
	v_mov_b32_e32 v79, v74
	v_mov_b32_e32 v74, v71
	v_pk_mul_f32 v[70:71], v[94:95], v[74:75]
	v_mov_b32_e32 v74, v72
	v_pk_fma_f32 v[70:71], v[92:93], v[78:79], v[70:71]
	v_mov_b32_e32 v75, v76
	v_pk_fma_f32 v[70:71], v[96:97], v[74:75], v[70:71]
	v_mov_b32_e32 v76, v73
	v_pk_fma_f32 v[70:71], v[100:101], v[76:77], v[70:71]
	s_nop 0
	v_add_f32_e32 v0, v0, v70
	v_add_f32_e32 v0, v0, v71
	v_min_f32_e32 v69, 0, v0
	v_mul_f32_e64 v0, |v0|, s30
	v_exp_f32_e32 v0, v0
	s_nop 0
	v_add_f32_e32 v0, 1.0, v0
	v_cmp_gt_f32_e64 s[0:1], s23, v0
	s_nop 1
	v_cndmask_b32_e64 v70, 0, 32, s[0:1]
	v_ldexp_f32 v0, v0, v70
	v_log_f32_e32 v0, v0
	s_nop 0
	v_mul_f32_e32 v70, 0x3f317217, v0
	v_fma_f32 v70, v0, s31, -v70
	v_fmac_f32_e32 v70, 0x3377d1cf, v0
	v_fmac_f32_e32 v70, 0x3f317217, v0
	v_cmp_lt_f32_e64 s[18:19], |v0|, s41
	s_nop 1
	v_cndmask_b32_e64 v0, v0, v70, s[18:19]
	v_cndmask_b32_e64 v70, 0, v223, s[0:1]
	v_sub_f32_e32 v0, v0, v70
	ds_read_b128 v[70:73], v118 offset:256
	ds_read_b128 v[74:77], v118 offset:272
	v_sub_f32_e32 v0, v69, v0
	v_fmamk_f32 v69, v0, 0x3d800000, v68
	s_waitcnt lgkmcnt(1)
	v_mov_b32_e32 v78, v70
	s_waitcnt lgkmcnt(0)
	v_mov_b32_e32 v79, v74
	v_mov_b32_e32 v74, v71
	v_pk_mul_f32 v[70:71], v[90:91], v[74:75]
	v_mov_b32_e32 v74, v72
	v_pk_fma_f32 v[70:71], v[88:89], v[78:79], v[70:71]
	v_mov_b32_e32 v75, v76
	v_pk_fma_f32 v[70:71], v[86:87], v[74:75], v[70:71]
	v_mov_b32_e32 v76, v73
	v_pk_fma_f32 v[70:71], v[98:99], v[76:77], v[70:71]
	s_nop 0
	v_add_f32_e32 v0, v117, v70
	v_add_f32_e32 v0, v0, v71
	ds_read_b128 v[70:73], v118 offset:288
	ds_read_b128 v[74:77], v118 offset:304
	s_waitcnt lgkmcnt(1)
	v_mov_b32_e32 v78, v70
	s_waitcnt lgkmcnt(0)
	v_mov_b32_e32 v79, v74
	v_mov_b32_e32 v74, v71
	v_pk_mul_f32 v[70:71], v[94:95], v[74:75]
	v_mov_b32_e32 v74, v72
	v_pk_fma_f32 v[70:71], v[92:93], v[78:79], v[70:71]
	v_mov_b32_e32 v75, v76
	v_pk_fma_f32 v[70:71], v[96:97], v[74:75], v[70:71]
	v_mov_b32_e32 v76, v73
	v_pk_fma_f32 v[70:71], v[100:101], v[76:77], v[70:71]
	ds_read_b128 v[72:75], v118 offset:320
	ds_read_b128 v[76:79], v118 offset:336
	v_add_f32_e32 v0, v0, v70
	v_add_f32_e32 v0, v0, v71
	v_min_f32_e32 v70, 0, v0
	v_mul_f32_e64 v0, |v0|, s30
	v_exp_f32_e32 v0, v0
	s_waitcnt lgkmcnt(0)
	v_mov_b32_e32 v81, v76
	v_mov_b32_e32 v76, v73
	v_mov_b32_e32 v80, v72
	v_add_f32_e32 v0, 1.0, v0
	v_cmp_gt_f32_e64 s[0:1], s23, v0
	v_pk_mul_f32 v[72:73], v[90:91], v[76:77]
	v_mov_b32_e32 v76, v74
	v_cndmask_b32_e64 v71, 0, 32, s[0:1]
	v_ldexp_f32 v0, v0, v71
	v_log_f32_e32 v0, v0
	v_pk_fma_f32 v[72:73], v[88:89], v[80:81], v[72:73]
	v_mov_b32_e32 v77, v78
	v_pk_fma_f32 v[72:73], v[86:87], v[76:77], v[72:73]
	v_mul_f32_e32 v71, 0x3f317217, v0
	v_fma_f32 v71, v0, s31, -v71
	v_fmac_f32_e32 v71, 0x3377d1cf, v0
	v_fmac_f32_e32 v71, 0x3f317217, v0
	v_cmp_lt_f32_e64 s[18:19], |v0|, s41
	v_mov_b32_e32 v78, v75
	v_pk_fma_f32 v[72:73], v[98:99], v[78:79], v[72:73]
	v_cndmask_b32_e64 v0, v0, v71, s[18:19]
	v_cndmask_b32_e64 v71, 0, v223, s[0:1]
	v_sub_f32_e32 v0, v0, v71
	v_sub_f32_e32 v0, v70, v0
	v_fmamk_f32 v70, v0, 0x3d800000, v69
	v_add_f32_e32 v0, v117, v72
	v_add_f32_e32 v0, v0, v73
	ds_read_b128 v[72:75], v118 offset:352
	ds_read_b128 v[76:79], v118 offset:368
	s_waitcnt lgkmcnt(1)
	v_mov_b32_e32 v80, v72
	s_waitcnt lgkmcnt(0)
	v_mov_b32_e32 v81, v76
	v_mov_b32_e32 v76, v73
	v_pk_mul_f32 v[72:73], v[94:95], v[76:77]
	v_mov_b32_e32 v76, v74
	v_pk_fma_f32 v[72:73], v[92:93], v[80:81], v[72:73]
	v_mov_b32_e32 v77, v78
	v_pk_fma_f32 v[72:73], v[96:97], v[76:77], v[72:73]
	v_mov_b32_e32 v78, v75
	v_pk_fma_f32 v[72:73], v[100:101], v[78:79], v[72:73]
	s_nop 0
	v_add_f32_e32 v0, v0, v72
	v_add_f32_e32 v0, v0, v73
	v_min_f32_e32 v71, 0, v0
	v_mul_f32_e64 v0, |v0|, s30
	v_exp_f32_e32 v0, v0
	s_nop 0
	v_add_f32_e32 v0, 1.0, v0
	v_cmp_gt_f32_e64 s[0:1], s23, v0
	s_nop 1
	v_cndmask_b32_e64 v72, 0, 32, s[0:1]
	v_ldexp_f32 v0, v0, v72
	v_log_f32_e32 v0, v0
	s_nop 0
	v_mul_f32_e32 v72, 0x3f317217, v0
	v_fma_f32 v72, v0, s31, -v72
	v_fmac_f32_e32 v72, 0x3377d1cf, v0
	v_fmac_f32_e32 v72, 0x3f317217, v0
	v_cmp_lt_f32_e64 s[18:19], |v0|, s41
	s_nop 1
	v_cndmask_b32_e64 v0, v0, v72, s[18:19]
	v_cndmask_b32_e64 v72, 0, v223, s[0:1]
	v_sub_f32_e32 v0, v0, v72
	ds_read_b128 v[72:75], v118 offset:384
	ds_read_b128 v[76:79], v118 offset:400
	v_sub_f32_e32 v0, v71, v0
	v_fmamk_f32 v71, v0, 0x3d800000, v70
	s_waitcnt lgkmcnt(1)
	v_mov_b32_e32 v80, v72
	s_waitcnt lgkmcnt(0)
	v_mov_b32_e32 v81, v76
	v_mov_b32_e32 v76, v73
	v_pk_mul_f32 v[72:73], v[90:91], v[76:77]
	v_mov_b32_e32 v76, v74
	v_pk_fma_f32 v[72:73], v[88:89], v[80:81], v[72:73]
	v_mov_b32_e32 v77, v78
	v_pk_fma_f32 v[72:73], v[86:87], v[76:77], v[72:73]
	v_mov_b32_e32 v78, v75
	v_pk_fma_f32 v[72:73], v[98:99], v[78:79], v[72:73]
	s_nop 0
	v_add_f32_e32 v0, v117, v72
	v_add_f32_e32 v0, v0, v73
	ds_read_b128 v[72:75], v118 offset:416
	ds_read_b128 v[76:79], v118 offset:432
	s_waitcnt lgkmcnt(1)
	v_mov_b32_e32 v80, v72
	s_waitcnt lgkmcnt(0)
	v_mov_b32_e32 v81, v76
	v_mov_b32_e32 v76, v73
	v_pk_mul_f32 v[72:73], v[94:95], v[76:77]
	v_mov_b32_e32 v76, v74
	v_pk_fma_f32 v[72:73], v[92:93], v[80:81], v[72:73]
	v_mov_b32_e32 v77, v78
	v_pk_fma_f32 v[72:73], v[96:97], v[76:77], v[72:73]
	v_mov_b32_e32 v78, v75
	v_pk_fma_f32 v[72:73], v[100:101], v[78:79], v[72:73]
	ds_read_b128 v[74:77], v118 offset:448
	ds_read_b128 v[78:81], v118 offset:464
	v_add_f32_e32 v0, v0, v72
	v_add_f32_e32 v0, v0, v73
	v_min_f32_e32 v72, 0, v0
	v_mul_f32_e64 v0, |v0|, s30
	v_exp_f32_e32 v0, v0
	s_waitcnt lgkmcnt(0)
	v_mov_b32_e32 v83, v78
	v_mov_b32_e32 v78, v75
	v_mov_b32_e32 v82, v74
	v_add_f32_e32 v0, 1.0, v0
	v_cmp_gt_f32_e64 s[0:1], s23, v0
	v_pk_mul_f32 v[74:75], v[90:91], v[78:79]
	v_mov_b32_e32 v78, v76
	v_cndmask_b32_e64 v73, 0, 32, s[0:1]
	v_ldexp_f32 v0, v0, v73
	v_log_f32_e32 v0, v0
	v_pk_fma_f32 v[74:75], v[88:89], v[82:83], v[74:75]
	v_mov_b32_e32 v79, v80
	v_pk_fma_f32 v[74:75], v[86:87], v[78:79], v[74:75]
	v_mul_f32_e32 v73, 0x3f317217, v0
	v_fma_f32 v73, v0, s31, -v73
	v_fmac_f32_e32 v73, 0x3377d1cf, v0
	v_fmac_f32_e32 v73, 0x3f317217, v0
	v_cmp_lt_f32_e64 s[18:19], |v0|, s41
	v_mov_b32_e32 v80, v77
	v_pk_fma_f32 v[74:75], v[98:99], v[80:81], v[74:75]
	v_cndmask_b32_e64 v0, v0, v73, s[18:19]
	v_cndmask_b32_e64 v73, 0, v223, s[0:1]
	v_sub_f32_e32 v0, v0, v73
	v_sub_f32_e32 v0, v72, v0
	v_fmamk_f32 v72, v0, 0x3d800000, v71
	v_add_f32_e32 v0, v117, v74
	v_add_f32_e32 v0, v0, v75
	ds_read_b128 v[74:77], v118 offset:480
	ds_read_b128 v[78:81], v118 offset:496
	s_waitcnt lgkmcnt(1)
	v_mov_b32_e32 v82, v74
	s_waitcnt lgkmcnt(0)
	v_mov_b32_e32 v83, v78
	v_mov_b32_e32 v78, v75
	v_pk_mul_f32 v[74:75], v[94:95], v[78:79]
	v_mov_b32_e32 v78, v76
	v_pk_fma_f32 v[74:75], v[92:93], v[82:83], v[74:75]
	v_mov_b32_e32 v79, v80
	v_pk_fma_f32 v[74:75], v[96:97], v[78:79], v[74:75]
	v_mov_b32_e32 v80, v77
	v_pk_fma_f32 v[74:75], v[100:101], v[80:81], v[74:75]
	s_nop 0
	v_add_f32_e32 v0, v0, v74
	v_add_f32_e32 v0, v0, v75
	v_min_f32_e32 v73, 0, v0
	v_mul_f32_e64 v0, |v0|, s30
	v_exp_f32_e32 v0, v0
	s_nop 0
	v_add_f32_e32 v0, 1.0, v0
	v_cmp_gt_f32_e64 s[0:1], s23, v0
	s_nop 1
	v_cndmask_b32_e64 v74, 0, 32, s[0:1]
	v_ldexp_f32 v0, v0, v74
	v_log_f32_e32 v0, v0
	s_nop 0
	v_mul_f32_e32 v74, 0x3f317217, v0
	v_fma_f32 v74, v0, s31, -v74
	v_fmac_f32_e32 v74, 0x3377d1cf, v0
	v_fmac_f32_e32 v74, 0x3f317217, v0
	v_cmp_lt_f32_e64 s[18:19], |v0|, s41
	s_nop 1
	v_cndmask_b32_e64 v0, v0, v74, s[18:19]
	v_cndmask_b32_e64 v74, 0, v223, s[0:1]
	v_sub_f32_e32 v0, v0, v74
	ds_read_b128 v[74:77], v118 offset:512
	ds_read_b128 v[78:81], v118 offset:528
	v_sub_f32_e32 v0, v73, v0
	v_fmamk_f32 v73, v0, 0x3d800000, v72
	s_waitcnt lgkmcnt(1)
	v_mov_b32_e32 v82, v74
	s_waitcnt lgkmcnt(0)
	v_mov_b32_e32 v83, v78
	v_mov_b32_e32 v78, v75
	v_pk_mul_f32 v[74:75], v[90:91], v[78:79]
	v_mov_b32_e32 v78, v76
	v_pk_fma_f32 v[74:75], v[88:89], v[82:83], v[74:75]
	v_mov_b32_e32 v79, v80
	v_pk_fma_f32 v[74:75], v[86:87], v[78:79], v[74:75]
	v_mov_b32_e32 v80, v77
	v_pk_fma_f32 v[74:75], v[98:99], v[80:81], v[74:75]
	s_nop 0
	v_add_f32_e32 v0, v117, v74
	v_add_f32_e32 v0, v0, v75
	ds_read_b128 v[74:77], v118 offset:544
	ds_read_b128 v[78:81], v118 offset:560
	s_waitcnt lgkmcnt(1)
	v_mov_b32_e32 v82, v74
	s_waitcnt lgkmcnt(0)
	v_mov_b32_e32 v83, v78
	v_mov_b32_e32 v78, v75
	v_pk_mul_f32 v[74:75], v[94:95], v[78:79]
	v_mov_b32_e32 v78, v76
	v_pk_fma_f32 v[74:75], v[92:93], v[82:83], v[74:75]
	v_mov_b32_e32 v79, v80
	v_pk_fma_f32 v[74:75], v[96:97], v[78:79], v[74:75]
	v_mov_b32_e32 v80, v77
	v_pk_fma_f32 v[74:75], v[100:101], v[80:81], v[74:75]
	ds_read_b128 v[78:81], v118 offset:576
	ds_read_b128 v[82:85], v118 offset:592
	v_add_f32_e32 v0, v0, v74
	v_add_f32_e32 v0, v0, v75
	v_min_f32_e32 v74, 0, v0
	v_mul_f32_e64 v0, |v0|, s30
	v_exp_f32_e32 v0, v0
	s_nop 0
	v_add_f32_e32 v0, 1.0, v0
	v_cmp_gt_f32_e64 s[0:1], s23, v0
	s_nop 1
	v_cndmask_b32_e64 v75, 0, 32, s[0:1]
	v_ldexp_f32 v0, v0, v75
	v_log_f32_e32 v0, v0
	s_nop 0
	v_mul_f32_e32 v75, 0x3f317217, v0
	v_fma_f32 v75, v0, s31, -v75
	v_fmac_f32_e32 v75, 0x3377d1cf, v0
	v_fmac_f32_e32 v75, 0x3f317217, v0
	v_cmp_lt_f32_e64 s[18:19], |v0|, s41
	s_nop 1
	v_cndmask_b32_e64 v0, v0, v75, s[18:19]
	v_cndmask_b32_e64 v75, 0, v223, s[0:1]
	v_sub_f32_e32 v0, v0, v75
	s_waitcnt lgkmcnt(0)
	v_mov_b32_e32 v75, v82
	v_mov_b32_e32 v82, v79
	v_sub_f32_e32 v0, v74, v0
	v_mov_b32_e32 v74, v78
	v_pk_mul_f32 v[78:79], v[90:91], v[82:83]
	v_fmamk_f32 v76, v0, 0x3d800000, v73
	v_pk_fma_f32 v[74:75], v[88:89], v[74:75], v[78:79]
	v_mov_b32_e32 v78, v80
	v_mov_b32_e32 v79, v84
	v_pk_fma_f32 v[74:75], v[86:87], v[78:79], v[74:75]
	v_mov_b32_e32 v84, v81
	v_pk_fma_f32 v[74:75], v[98:99], v[84:85], v[74:75]
	ds_read_b128 v[78:81], v118 offset:608
	ds_read_b128 v[82:85], v118 offset:624
	v_add_f32_e32 v0, v117, v74
	v_add_f32_e32 v0, v0, v75
	s_waitcnt lgkmcnt(1)
	v_mov_b32_e32 v74, v78
	s_waitcnt lgkmcnt(0)
	v_mov_b32_e32 v75, v82
	v_mov_b32_e32 v82, v79
	v_pk_mul_f32 v[78:79], v[94:95], v[82:83]
	s_nop 0
	v_pk_fma_f32 v[74:75], v[92:93], v[74:75], v[78:79]
	v_mov_b32_e32 v78, v80
	v_mov_b32_e32 v79, v84
	v_pk_fma_f32 v[74:75], v[96:97], v[78:79], v[74:75]
	v_mov_b32_e32 v84, v81
	v_pk_fma_f32 v[74:75], v[100:101], v[84:85], v[74:75]
	ds_read_b128 v[78:81], v118 offset:640
	ds_read_b128 v[82:85], v118 offset:656
	v_add_f32_e32 v0, v0, v74
	v_add_f32_e32 v0, v0, v75
	v_min_f32_e32 v74, 0, v0
	v_mul_f32_e64 v0, |v0|, s30
	v_exp_f32_e32 v0, v0
	s_nop 0
	v_add_f32_e32 v0, 1.0, v0
	v_cmp_gt_f32_e64 s[0:1], s23, v0
	s_nop 1
	v_cndmask_b32_e64 v75, 0, 32, s[0:1]
	v_ldexp_f32 v0, v0, v75
	v_log_f32_e32 v0, v0
	s_nop 0
	v_mul_f32_e32 v75, 0x3f317217, v0
	v_fma_f32 v75, v0, s31, -v75
	v_fmac_f32_e32 v75, 0x3377d1cf, v0
	v_fmac_f32_e32 v75, 0x3f317217, v0
	v_cmp_lt_f32_e64 s[18:19], |v0|, s41
	s_nop 1
	v_cndmask_b32_e64 v0, v0, v75, s[18:19]
	v_cndmask_b32_e64 v75, 0, v223, s[0:1]
	v_sub_f32_e32 v0, v0, v75
	s_waitcnt lgkmcnt(0)
	v_mov_b32_e32 v75, v82
	v_mov_b32_e32 v82, v79
	v_sub_f32_e32 v0, v74, v0
	v_mov_b32_e32 v74, v78
	v_pk_mul_f32 v[78:79], v[90:91], v[82:83]
	v_fmamk_f32 v77, v0, 0x3d800000, v76
	v_pk_fma_f32 v[74:75], v[88:89], v[74:75], v[78:79]
	v_mov_b32_e32 v78, v80
	v_mov_b32_e32 v79, v84
	v_pk_fma_f32 v[74:75], v[86:87], v[78:79], v[74:75]
	v_mov_b32_e32 v84, v81
	v_pk_fma_f32 v[74:75], v[98:99], v[84:85], v[74:75]
	ds_read_b128 v[78:81], v118 offset:672
	ds_read_b128 v[82:85], v118 offset:688
	v_add_f32_e32 v0, v117, v74
	v_add_f32_e32 v0, v0, v75
	s_waitcnt lgkmcnt(1)
	v_mov_b32_e32 v74, v78
	s_waitcnt lgkmcnt(0)
	v_mov_b32_e32 v75, v82
	v_mov_b32_e32 v82, v79
	v_pk_mul_f32 v[78:79], v[94:95], v[82:83]
	s_nop 0
	v_pk_fma_f32 v[74:75], v[92:93], v[74:75], v[78:79]
	v_mov_b32_e32 v78, v80
	v_mov_b32_e32 v79, v84
	v_pk_fma_f32 v[74:75], v[96:97], v[78:79], v[74:75]
	v_mov_b32_e32 v84, v81
	v_pk_fma_f32 v[74:75], v[100:101], v[84:85], v[74:75]
	ds_read_b128 v[80:83], v118 offset:704
	ds_read_b128 v[134:137], v118 offset:720
	v_add_f32_e32 v0, v0, v74
	v_add_f32_e32 v0, v0, v75
	v_min_f32_e32 v74, 0, v0
	v_mul_f32_e64 v0, |v0|, s30
	v_exp_f32_e32 v0, v0
	s_nop 0
	v_add_f32_e32 v0, 1.0, v0
	v_cmp_gt_f32_e64 s[0:1], s23, v0
	s_nop 1
	v_cndmask_b32_e64 v75, 0, 32, s[0:1]
	v_ldexp_f32 v0, v0, v75
	v_log_f32_e32 v0, v0
	s_nop 0
	v_mul_f32_e32 v75, 0x3f317217, v0
	v_fma_f32 v75, v0, s31, -v75
	v_fmac_f32_e32 v75, 0x3377d1cf, v0
	v_fmac_f32_e32 v75, 0x3f317217, v0
	v_cmp_lt_f32_e64 s[18:19], |v0|, s41
	s_nop 1
	v_cndmask_b32_e64 v0, v0, v75, s[18:19]
	v_cndmask_b32_e64 v75, 0, v223, s[0:1]
	v_sub_f32_e32 v0, v0, v75
	s_waitcnt lgkmcnt(0)
	v_mov_b32_e32 v75, v134
	v_mov_b32_e32 v134, v81
	v_sub_f32_e32 v0, v74, v0
	v_mov_b32_e32 v74, v80
	v_pk_mul_f32 v[80:81], v[90:91], v[134:135]
	v_fmamk_f32 v78, v0, 0x3d800000, v77
	v_pk_fma_f32 v[74:75], v[88:89], v[74:75], v[80:81]
	v_mov_b32_e32 v80, v82
	v_mov_b32_e32 v81, v136
	v_pk_fma_f32 v[74:75], v[86:87], v[80:81], v[74:75]
	v_mov_b32_e32 v136, v83
	v_pk_fma_f32 v[74:75], v[98:99], v[136:137], v[74:75]
	ds_read_b128 v[80:83], v118 offset:736
	ds_read_b128 v[134:137], v118 offset:752
	v_add_f32_e32 v0, v117, v74
	v_add_f32_e32 v0, v0, v75
	s_waitcnt lgkmcnt(1)
	v_mov_b32_e32 v74, v80
	s_waitcnt lgkmcnt(0)
	v_mov_b32_e32 v75, v134
	v_mov_b32_e32 v134, v81
	v_pk_mul_f32 v[80:81], v[94:95], v[134:135]
	s_nop 0
	v_pk_fma_f32 v[74:75], v[92:93], v[74:75], v[80:81]
	v_mov_b32_e32 v80, v82
	v_mov_b32_e32 v81, v136
	v_pk_fma_f32 v[74:75], v[96:97], v[80:81], v[74:75]
	v_mov_b32_e32 v136, v83
	v_pk_fma_f32 v[74:75], v[100:101], v[136:137], v[74:75]
	ds_read_b128 v[80:83], v118 offset:768
	ds_read_b128 v[134:137], v118 offset:784
	v_add_f32_e32 v0, v0, v74
	v_add_f32_e32 v0, v0, v75
	v_min_f32_e32 v74, 0, v0
	v_mul_f32_e64 v0, |v0|, s30
	v_exp_f32_e32 v0, v0
	s_nop 0
	v_add_f32_e32 v0, 1.0, v0
	v_cmp_gt_f32_e64 s[0:1], s23, v0
	s_nop 1
	v_cndmask_b32_e64 v75, 0, 32, s[0:1]
	v_ldexp_f32 v0, v0, v75
	v_log_f32_e32 v0, v0
	s_nop 0
	v_mul_f32_e32 v75, 0x3f317217, v0
	v_fma_f32 v75, v0, s31, -v75
	v_fmac_f32_e32 v75, 0x3377d1cf, v0
	v_fmac_f32_e32 v75, 0x3f317217, v0
	v_cmp_lt_f32_e64 s[18:19], |v0|, s41
	s_nop 1
	v_cndmask_b32_e64 v0, v0, v75, s[18:19]
	v_cndmask_b32_e64 v75, 0, v223, s[0:1]
	v_sub_f32_e32 v0, v0, v75
	s_waitcnt lgkmcnt(0)
	v_mov_b32_e32 v75, v134
	v_mov_b32_e32 v134, v81
	v_sub_f32_e32 v0, v74, v0
	v_mov_b32_e32 v74, v80
	v_pk_mul_f32 v[80:81], v[90:91], v[134:135]
	v_fmamk_f32 v79, v0, 0x3d800000, v78
	v_pk_fma_f32 v[74:75], v[88:89], v[74:75], v[80:81]
	v_mov_b32_e32 v80, v82
	v_mov_b32_e32 v81, v136
	v_pk_fma_f32 v[74:75], v[86:87], v[80:81], v[74:75]
	v_mov_b32_e32 v136, v83
	v_pk_fma_f32 v[74:75], v[98:99], v[136:137], v[74:75]
	ds_read_b128 v[80:83], v118 offset:800
	ds_read_b128 v[134:137], v118 offset:816
	v_add_f32_e32 v0, v117, v74
	v_add_f32_e32 v0, v0, v75
	s_waitcnt lgkmcnt(1)
	v_mov_b32_e32 v74, v80
	s_waitcnt lgkmcnt(0)
	v_mov_b32_e32 v75, v134
	v_mov_b32_e32 v134, v81
	v_pk_mul_f32 v[80:81], v[94:95], v[134:135]
	s_nop 0
	v_pk_fma_f32 v[74:75], v[92:93], v[74:75], v[80:81]
	v_mov_b32_e32 v80, v82
	v_mov_b32_e32 v81, v136
	v_pk_fma_f32 v[74:75], v[96:97], v[80:81], v[74:75]
	v_mov_b32_e32 v136, v83
	v_pk_fma_f32 v[74:75], v[100:101], v[136:137], v[74:75]
	ds_read_b128 v[82:85], v118 offset:832
	ds_read_b128 v[134:137], v118 offset:848
	v_add_f32_e32 v0, v0, v74
	v_add_f32_e32 v0, v0, v75
	v_min_f32_e32 v74, 0, v0
	v_mul_f32_e64 v0, |v0|, s30
	v_exp_f32_e32 v0, v0
	s_nop 0
	v_add_f32_e32 v0, 1.0, v0
	v_cmp_gt_f32_e64 s[0:1], s23, v0
	s_nop 1
	v_cndmask_b32_e64 v75, 0, 32, s[0:1]
	v_ldexp_f32 v0, v0, v75
	v_log_f32_e32 v0, v0
	s_nop 0
	v_mul_f32_e32 v75, 0x3f317217, v0
	v_fma_f32 v75, v0, s31, -v75
	v_fmac_f32_e32 v75, 0x3377d1cf, v0
	v_fmac_f32_e32 v75, 0x3f317217, v0
	v_cmp_lt_f32_e64 s[18:19], |v0|, s41
	s_nop 1
	v_cndmask_b32_e64 v0, v0, v75, s[18:19]
	v_cndmask_b32_e64 v75, 0, v223, s[0:1]
	v_sub_f32_e32 v0, v0, v75
	s_waitcnt lgkmcnt(0)
	v_mov_b32_e32 v75, v134
	v_mov_b32_e32 v134, v83
	v_sub_f32_e32 v0, v74, v0
	v_mov_b32_e32 v74, v82
	v_pk_mul_f32 v[82:83], v[90:91], v[134:135]
	v_fmamk_f32 v80, v0, 0x3d800000, v79
	v_pk_fma_f32 v[74:75], v[88:89], v[74:75], v[82:83]
	v_mov_b32_e32 v82, v84
	v_mov_b32_e32 v83, v136
	v_pk_fma_f32 v[74:75], v[86:87], v[82:83], v[74:75]
	v_mov_b32_e32 v136, v85
	v_pk_fma_f32 v[74:75], v[98:99], v[136:137], v[74:75]
	ds_read_b128 v[82:85], v118 offset:864
	ds_read_b128 v[134:137], v118 offset:880
	v_add_f32_e32 v0, v117, v74
	v_add_f32_e32 v0, v0, v75
	s_waitcnt lgkmcnt(1)
	v_mov_b32_e32 v74, v82
	s_waitcnt lgkmcnt(0)
	v_mov_b32_e32 v75, v134
	v_mov_b32_e32 v134, v83
	v_pk_mul_f32 v[82:83], v[94:95], v[134:135]
	s_nop 0
	v_pk_fma_f32 v[74:75], v[92:93], v[74:75], v[82:83]
	v_mov_b32_e32 v82, v84
	v_mov_b32_e32 v83, v136
	v_pk_fma_f32 v[74:75], v[96:97], v[82:83], v[74:75]
	v_mov_b32_e32 v136, v85
	v_pk_fma_f32 v[74:75], v[100:101], v[136:137], v[74:75]
	ds_read_b128 v[134:137], v118 offset:896
	ds_read_b128 v[138:141], v118 offset:912
	v_add_f32_e32 v0, v0, v74
	v_add_f32_e32 v0, v0, v75
	v_min_f32_e32 v74, 0, v0
	v_mul_f32_e64 v0, |v0|, s30
	v_exp_f32_e32 v0, v0
	s_nop 0
	v_add_f32_e32 v0, 1.0, v0
	v_cmp_gt_f32_e64 s[0:1], s23, v0
	s_nop 1
	v_cndmask_b32_e64 v75, 0, 32, s[0:1]
	v_ldexp_f32 v0, v0, v75
	v_log_f32_e32 v0, v0
	s_nop 0
	v_mul_f32_e32 v75, 0x3f317217, v0
	v_fma_f32 v75, v0, s31, -v75
	v_fmac_f32_e32 v75, 0x3377d1cf, v0
	v_fmac_f32_e32 v75, 0x3f317217, v0
	v_cmp_lt_f32_e64 s[18:19], |v0|, s41
	s_nop 1
	v_cndmask_b32_e64 v0, v0, v75, s[18:19]
	v_cndmask_b32_e64 v75, 0, v223, s[0:1]
	v_sub_f32_e32 v0, v0, v75
	s_waitcnt lgkmcnt(0)
	v_mov_b32_e32 v75, v138
	v_mov_b32_e32 v138, v135
	v_sub_f32_e32 v0, v74, v0
	v_mov_b32_e32 v74, v134
	v_pk_mul_f32 v[84:85], v[90:91], v[138:139]
	v_fmamk_f32 v82, v0, 0x3d800000, v80
	v_pk_fma_f32 v[74:75], v[88:89], v[74:75], v[84:85]
	v_mov_b32_e32 v84, v136
	v_mov_b32_e32 v85, v140
	v_pk_fma_f32 v[74:75], v[86:87], v[84:85], v[74:75]
	v_mov_b32_e32 v140, v137
	v_pk_fma_f32 v[74:75], v[98:99], v[140:141], v[74:75]
	ds_read_b128 v[134:137], v118 offset:928
	ds_read_b128 v[138:141], v118 offset:944
	v_add_f32_e32 v0, v117, v74
	v_add_f32_e32 v0, v0, v75
	s_waitcnt lgkmcnt(1)
	v_mov_b32_e32 v74, v134
	s_waitcnt lgkmcnt(0)
	v_mov_b32_e32 v75, v138
	v_mov_b32_e32 v138, v135
	v_pk_mul_f32 v[84:85], v[94:95], v[138:139]
	s_nop 0
	v_pk_fma_f32 v[74:75], v[92:93], v[74:75], v[84:85]
	v_mov_b32_e32 v84, v136
	v_mov_b32_e32 v85, v140
	v_pk_fma_f32 v[74:75], v[96:97], v[84:85], v[74:75]
	v_mov_b32_e32 v140, v137
	v_pk_fma_f32 v[74:75], v[100:101], v[140:141], v[74:75]
	ds_read_b128 v[134:137], v118 offset:960
	ds_read_b128 v[138:141], v118 offset:976
	v_add_f32_e32 v0, v0, v74
	v_add_f32_e32 v0, v0, v75
	v_min_f32_e32 v74, 0, v0
	v_mul_f32_e64 v0, |v0|, s30
	v_exp_f32_e32 v0, v0
	s_nop 0
	v_add_f32_e32 v0, 1.0, v0
	v_cmp_gt_f32_e64 s[0:1], s23, v0
	s_nop 1
	v_cndmask_b32_e64 v75, 0, 32, s[0:1]
	v_ldexp_f32 v0, v0, v75
	v_log_f32_e32 v0, v0
	s_nop 0
	v_mul_f32_e32 v75, 0x3f317217, v0
	v_fma_f32 v75, v0, s31, -v75
	v_fmac_f32_e32 v75, 0x3377d1cf, v0
	v_fmac_f32_e32 v75, 0x3f317217, v0
	v_cmp_lt_f32_e64 s[18:19], |v0|, s41
	s_nop 1
	v_cndmask_b32_e64 v0, v0, v75, s[18:19]
	v_cndmask_b32_e64 v75, 0, v223, s[0:1]
	v_sub_f32_e32 v0, v0, v75
	s_waitcnt lgkmcnt(0)
	v_mov_b32_e32 v75, v138
	v_mov_b32_e32 v138, v135
	v_sub_f32_e32 v0, v74, v0
	v_mov_b32_e32 v74, v134
	v_pk_mul_f32 v[84:85], v[90:91], v[138:139]
	v_fmamk_f32 v83, v0, 0x3d800000, v82
	v_pk_fma_f32 v[74:75], v[88:89], v[74:75], v[84:85]
	v_mov_b32_e32 v84, v136
	v_mov_b32_e32 v85, v140
	v_pk_fma_f32 v[74:75], v[86:87], v[84:85], v[74:75]
	v_mov_b32_e32 v140, v137
	v_pk_fma_f32 v[74:75], v[98:99], v[140:141], v[74:75]
	ds_read_b128 v[134:137], v118 offset:992
	ds_read_b128 v[138:141], v118 offset:1008
	v_add_f32_e32 v0, v117, v74
	v_add_f32_e32 v0, v0, v75
	s_waitcnt lgkmcnt(1)
	v_mov_b32_e32 v74, v134
	s_waitcnt lgkmcnt(0)
	v_mov_b32_e32 v75, v138
	v_mov_b32_e32 v138, v135
	v_pk_mul_f32 v[84:85], v[94:95], v[138:139]
	s_nop 0
	v_pk_fma_f32 v[74:75], v[92:93], v[74:75], v[84:85]
	v_mov_b32_e32 v84, v136
	v_mov_b32_e32 v85, v140
	v_pk_fma_f32 v[74:75], v[96:97], v[84:85], v[74:75]
	v_mov_b32_e32 v140, v137
	v_pk_fma_f32 v[74:75], v[100:101], v[140:141], v[74:75]
	s_nop 0
	v_add_f32_e32 v0, v0, v74
	v_add_f32_e32 v0, v0, v75
	v_min_f32_e32 v74, 0, v0
	v_mul_f32_e64 v0, |v0|, s30
	v_exp_f32_e32 v0, v0
	s_nop 0
	v_add_f32_e32 v0, 1.0, v0
	v_cmp_gt_f32_e64 s[0:1], s23, v0
	s_nop 1
	v_cndmask_b32_e64 v75, 0, 32, s[0:1]
	v_ldexp_f32 v0, v0, v75
	v_log_f32_e32 v0, v0
	s_nop 0
	v_mul_f32_e32 v75, 0x3f317217, v0
	v_fma_f32 v75, v0, s31, -v75
	v_fmac_f32_e32 v75, 0x3377d1cf, v0
	v_fmac_f32_e32 v75, 0x3f317217, v0
	v_cmp_lt_f32_e64 s[18:19], |v0|, s41
	s_nop 1
	v_cndmask_b32_e64 v0, v0, v75, s[18:19]
	v_cndmask_b32_e64 v75, 0, v223, s[0:1]
	v_sub_f32_e32 v0, v0, v75
	v_sub_f32_e32 v0, v74, v0
	v_fmamk_f32 v84, v0, 0x3d800000, v83
	ds_write_b32 v119, v84 offset:4096
	s_waitcnt lgkmcnt(0)
	s_barrier
	ds_read2st64_b32 v[74:75], v120 offset0:16 offset1:18
	s_waitcnt lgkmcnt(0)
	v_add_f32_e32 v0, 0, v74
	v_cndmask_b32_e64 v74, 0, v0, s[10:11]
	v_add_f32_e32 v0, v0, v75
	v_add_f32_e32 v75, v75, v74
	v_cndmask_b32_e64 v81, v74, v75, s[12:13]
	ds_read2st64_b32 v[74:75], v120 offset0:20 offset1:22
	s_waitcnt lgkmcnt(0)
	v_add_f32_e32 v0, v0, v74
	v_add_f32_e32 v74, v74, v81
	v_cndmask_b32_e64 v74, v81, v74, s[14:15]
	v_add_f32_e32 v81, v0, v75
	v_add_f32_e32 v0, v75, v74
	v_cndmask_b32_e64 v85, v74, v0, s[16:17]
	v_add_u32_e32 v74, s5, v125
	v_ashrrev_i32_e32 v75, 31, v74
	v_add_u32_e32 v136, 1, v74
	v_lshlrev_b64 v[134:135], 11, v[74:75]
	v_ashrrev_i32_e32 v137, 31, v136
	v_lshl_add_u64 v[134:135], v[102:103], 0, v[134:135]
	v_lshlrev_b64 v[136:137], 11, v[136:137]
	v_lshl_add_u64 v[136:137], v[102:103], 0, v[136:137]
	s_waitcnt vmcnt(4)
	v_mov_b32_e32 v75, v170
	v_mov_b32_e32 v133, v171
	v_add_f32_e32 v66, v66, v85
	v_add_f32_e32 v67, v67, v85
	v_mul_f32_e32 v66, 0xbfb8aa3b, v66
	v_mul_f32_e32 v67, 0xbfb8aa3b, v67
	v_mul_f32_e32 v0, 0x3fb8aa3b, v81
	v_exp_f32_e32 v66, v66
	v_exp_f32_e32 v67, v67
	v_exp_f32_e32 v0, v0
	v_add_u32_e32 v136, 3, v74
	v_ashrrev_i32_e32 v137, 31, v136
	v_lshlrev_b64 v[136:137], 11, v[136:137]
	v_lshl_add_u64 v[136:137], v[102:103], 0, v[136:137]
	v_add_f32_e32 v70, v70, v85
	v_add_f32_e32 v71, v71, v85
	v_mul_f32_e32 v70, 0xbfb8aa3b, v70
	v_mul_f32_e32 v71, 0xbfb8aa3b, v71
	v_exp_f32_e32 v70, v70
	v_exp_f32_e32 v71, v71
	s_waitcnt vmcnt(1)
	v_lshlrev_b32_e32 v134, 16, v75
	s_waitcnt vmcnt(0)
	v_lshlrev_b32_e32 v135, 16, v133
	v_pk_mul_f32 v[66:67], v[66:67], v[134:135]
	v_add_u32_e32 v134, 2, v74
	v_pk_mul_f32 v[66:67], v[0:1], v[66:67] op_sel_hi:[0,1]
	v_cvt_pk_bf16_f32 v66, v66, v67
	v_add_f32_e32 v67, v68, v85
	v_ashrrev_i32_e32 v135, 31, v134
	v_mul_f32_e32 v67, 0xbfb8aa3b, v67
	v_lshlrev_b64 v[134:135], 11, v[134:135]
	v_exp_f32_e32 v68, v67
	v_add_f32_e32 v67, v69, v85
	v_lshl_add_u64 v[134:135], v[102:103], 0, v[134:135]
	v_mul_f32_e32 v67, 0xbfb8aa3b, v67
	v_exp_f32_e32 v69, v67
	v_mov_b32_e32 v67, v172
	v_mov_b32_e32 v75, v178
	s_waitcnt vmcnt(1)
	v_lshlrev_b32_e32 v134, 16, v67
	s_waitcnt vmcnt(0)
	v_lshlrev_b32_e32 v135, 16, v75
	v_pk_mul_f32 v[68:69], v[68:69], v[134:135]
	v_add_u32_e32 v134, 5, v74
	v_pk_mul_f32 v[68:69], v[0:1], v[68:69] op_sel_hi:[0,1]
	v_cvt_pk_bf16_f32 v67, v68, v69
	v_add_u32_e32 v68, 4, v74
	v_ashrrev_i32_e32 v69, 31, v68
	v_lshlrev_b64 v[68:69], 11, v[68:69]
	v_ashrrev_i32_e32 v135, 31, v134
	v_lshl_add_u64 v[68:69], v[102:103], 0, v[68:69]
	v_lshlrev_b64 v[134:135], 11, v[134:135]
	v_lshl_add_u64 v[134:135], v[102:103], 0, v[134:135]
	v_mov_b32_e32 v68, v181
	s_nop 0
	v_mov_b32_e32 v69, v202
	v_add_u32_e32 v134, 7, v74
	v_ashrrev_i32_e32 v135, 31, v134
	v_lshlrev_b64 v[134:135], 11, v[134:135]
	v_lshl_add_u64 v[134:135], v[102:103], 0, v[134:135]
	v_add_f32_e32 v75, v80, v85
	v_mul_f32_e32 v75, 0xbfb8aa3b, v75
	s_waitcnt vmcnt(1)
	v_lshlrev_b32_e32 v68, 16, v68
	s_waitcnt vmcnt(0)
	v_lshlrev_b32_e32 v69, 16, v69
	v_pk_mul_f32 v[68:69], v[70:71], v[68:69]
	v_add_u32_e32 v70, 6, v74
	v_pk_mul_f32 v[68:69], v[0:1], v[68:69] op_sel_hi:[0,1]
	v_cvt_pk_bf16_f32 v68, v68, v69
	v_add_f32_e32 v69, v72, v85
	v_ashrrev_i32_e32 v71, 31, v70
	v_mul_f32_e32 v69, 0xbfb8aa3b, v69
	v_lshlrev_b64 v[70:71], 11, v[70:71]
	v_exp_f32_e32 v72, v69
	v_add_f32_e32 v69, v73, v85
	v_lshl_add_u64 v[70:71], v[102:103], 0, v[70:71]
	v_mul_f32_e32 v69, 0xbfb8aa3b, v69
	v_exp_f32_e32 v73, v69
	v_mov_b32_e32 v69, v203
	s_nop 0
	v_mov_b32_e32 v70, v225
	s_waitcnt vmcnt(0)
	v_lshlrev_b32_e32 v71, 16, v70
	v_lshlrev_b32_e32 v70, 16, v69
	v_pk_mul_f32 v[70:71], v[72:73], v[70:71]
	v_add_f32_e32 v72, v76, v85
	v_pk_mul_f32 v[70:71], v[0:1], v[70:71] op_sel_hi:[0,1]
	v_cvt_pk_bf16_f32 v69, v70, v71
	v_add_u32_e32 v70, 8, v74
	v_ashrrev_i32_e32 v71, 31, v70
	v_add_u32_e32 v76, 9, v74
	v_lshlrev_b64 v[70:71], 11, v[70:71]
	v_add_f32_e32 v73, v77, v85
	v_ashrrev_i32_e32 v77, 31, v76
	v_lshl_add_u64 v[70:71], v[102:103], 0, v[70:71]
	v_lshlrev_b64 v[76:77], 11, v[76:77]
	v_lshl_add_u64 v[76:77], v[102:103], 0, v[76:77]
	v_mov_b32_e32 v70, v230
	s_nop 0
	v_mov_b32_e32 v71, v231
	v_mul_f32_e32 v72, 0xbfb8aa3b, v72
	v_mul_f32_e32 v73, 0xbfb8aa3b, v73
	v_exp_f32_e32 v72, v72
	v_exp_f32_e32 v73, v73
	s_waitcnt vmcnt(1)
	v_lshlrev_b32_e32 v70, 16, v70
	s_waitcnt vmcnt(0)
	v_lshlrev_b32_e32 v71, 16, v71
	v_pk_mul_f32 v[70:71], v[72:73], v[70:71]
	v_add_u32_e32 v72, 10, v74
	v_pk_mul_f32 v[70:71], v[0:1], v[70:71] op_sel_hi:[0,1]
	v_cvt_pk_bf16_f32 v70, v70, v71
	v_add_f32_e32 v71, v78, v85
	v_ashrrev_i32_e32 v73, 31, v72
	v_mul_f32_e32 v71, 0xbfb8aa3b, v71
	v_add_u32_e32 v78, 11, v74
	v_lshlrev_b64 v[72:73], 11, v[72:73]
	v_exp_f32_e32 v76, v71
	v_add_f32_e32 v71, v79, v85
	v_ashrrev_i32_e32 v79, 31, v78
	v_lshl_add_u64 v[72:73], v[102:103], 0, v[72:73]
	v_lshlrev_b64 v[78:79], 11, v[78:79]
	v_mul_f32_e32 v71, 0xbfb8aa3b, v71
	v_lshl_add_u64 v[78:79], v[102:103], 0, v[78:79]
	v_exp_f32_e32 v77, v71
	v_mov_b32_e32 v71, v236
	s_nop 0
	v_mov_b32_e32 v72, v237
	v_add_u32_e32 v78, 13, v74
	v_ashrrev_i32_e32 v79, 31, v78
	v_lshlrev_b64 v[78:79], 11, v[78:79]
	v_lshl_add_u64 v[78:79], v[102:103], 0, v[78:79]
	s_waitcnt vmcnt(0)
	v_lshlrev_b32_e32 v73, 16, v72
	v_lshlrev_b32_e32 v72, 16, v71
	v_pk_mul_f32 v[72:73], v[76:77], v[72:73]
	v_exp_f32_e32 v76, v75
	v_pk_mul_f32 v[72:73], v[0:1], v[72:73] op_sel_hi:[0,1]
	v_cvt_pk_bf16_f32 v71, v72, v73
	v_add_u32_e32 v72, 12, v74
	v_ashrrev_i32_e32 v73, 31, v72
	v_lshlrev_b64 v[72:73], 11, v[72:73]
	v_lshl_add_u64 v[72:73], v[102:103], 0, v[72:73]
	v_mov_b32_e32 v72, v238
	s_nop 0
	v_mov_b32_e32 v73, v241
	v_add_f32_e32 v75, v82, v85
	v_mul_f32_e32 v75, 0xbfb8aa3b, v75
	v_exp_f32_e32 v77, v75
	s_waitcnt vmcnt(1)
	v_lshlrev_b32_e32 v72, 16, v72
	s_waitcnt vmcnt(0)
	v_lshlrev_b32_e32 v73, 16, v73
	v_pk_mul_f32 v[72:73], v[76:77], v[72:73]
	v_add_u32_e32 v76, 14, v74
	v_pk_mul_f32 v[72:73], v[0:1], v[72:73] op_sel_hi:[0,1]
	v_cvt_pk_bf16_f32 v72, v72, v73
	v_add_f32_e32 v73, v83, v85
	v_ashrrev_i32_e32 v77, 31, v76
	v_add_u32_e32 v74, 15, v74
	v_lshlrev_b64 v[76:77], 11, v[76:77]
	v_mul_f32_e32 v73, 0xbfb8aa3b, v73
	v_ashrrev_i32_e32 v75, 31, v74
	v_lshl_add_u64 v[78:79], v[102:103], 0, v[76:77]
	v_exp_f32_e32 v76, v73
	v_add_f32_e32 v73, v85, v84
	v_lshlrev_b64 v[74:75], 11, v[74:75]
	v_lshl_add_u64 v[74:75], v[102:103], 0, v[74:75]
	v_mul_f32_e32 v73, 0xbfb8aa3b, v73
	v_exp_f32_e32 v77, v73
	v_mov_b32_e32 v73, v242
	s_nop 0
	v_mov_b32_e32 v74, v243
	s_waitcnt vmcnt(0)
	v_lshlrev_b32_e32 v75, 16, v74
	v_lshlrev_b32_e32 v74, 16, v73
	v_pk_mul_f32 v[74:75], v[76:77], v[74:75]
	s_nop 0
	v_pk_mul_f32 v[74:75], v[0:1], v[74:75] op_sel_hi:[0,1]
	v_cvt_pk_bf16_f32 v73, v74, v75
	ds_write_b128 v127, v[66:69] offset:43520
	ds_write_b128 v127, v[70:73] offset:43536
	s_and_saveexec_b64 s[0:1], s[8:9]
	s_cbranch_execz .LBB0_153
	v_mul_f32_e32 v115, v115, v0
	ds_write_b32 v128, v81 offset:6144
	s_branch .LBB0_153
